# base21 + P0 adaLN mat-vec loop: weight prefetch overlaps one full iteration (wait moved to the register rotation)
# speedup vs baseline: 1.0046x; 1.0046x over previous
; #define LAS __attribute__((address_space(3)))
; __device__ __forceinline__ void phase_prologue(const Args& a, LAS unsigned char* lds, const WCtx& w) {
;     ...
;         for (int it = w.bid; it < 4 * 96; it += w.G) {
;             const int l = it / 96, cg = it - l * 96;
;             const float* wp = a.in[I_ADAW] + (size_t)l * 1024 * 6144 + cg * 64 + w.lane;
;             float acc[17];
; #pragma unroll
;             for (int r = 0; r < 17; ++r) acc[r] = 0.f;
;             const int k0 = w.wave * 128;
;             const float* wq = wp + (size_t)k0 * 6144;
;             float a0 = wq[0], a1 = wq[6144], a2 = wq[2 * 6144], a3 = wq[3 * 6144], b0 = wq[4 * 6144], b1 = wq[5 * 6144], b2 = wq[6 * 6144], b3 = wq[7 * 6144];
; #pragma unroll 1
;             for (int k = k0; k < k0 + 128; k += 4) {
;                 const float w0 = a0, w1 = a1, w2 = a2, w3 = a3; a0 = b0; a1 = b1; a2 = b2; a3 = b3;
;                 if (k + 8 < k0 + 128) { const float* wn = wp + (size_t)(k + 8) * 6144; b0 = wn[0]; b1 = wn[6144]; b2 = wn[2 * 6144]; b3 = wn[3 * 6144]; }
; #pragma unroll
;                 for (int r = 0; r < 17; ++r) { const f32x4 s = *(const LAS f32x4*)(SC + r * 1024 + k); acc[r] += (s[0] * w0 + s[1] * w1) + (s[2] * w2 + s[3] * w3); }
;             }
.LBB0_21:
	s_mul_hi_i32 s6, s19, 0x2aaaaaab
	s_lshr_b32 s7, s6, 31
	s_ashr_i32 s20, s6, 4
	s_add_i32 s20, s20, s7
	s_load_dwordx16 s[56:71], s[0:1], 0x0
	s_mul_i32 s6, s20, 0xffffffa0
	s_add_i32 s6, s6, s19
	s_lshl_b32 s6, s6, 6
	s_mul_i32 s9, s20, 0x1800000
	s_ashr_i32 s7, s6, 31
	s_mul_hi_i32 s8, s20, 0x1800000
	s_waitcnt lgkmcnt(0)
	s_add_u32 s22, s64, s9
	s_addc_u32 s24, s65, s8
	s_lshl_b64 s[8:9], s[6:7], 2
	s_add_u32 s8, s22, s8
	s_addc_u32 s9, s24, s9
	v_lshl_add_u64 v[8:9], s[8:9], 0, v[4:5]
	v_lshl_add_u64 v[10:11], v[8:9], 0, s[2:3]
	v_add_co_u32_e32 v12, vcc, s11, v10
	s_mov_b32 s8, s14
	s_nop 0
	v_addc_co_u32_e32 v13, vcc, 0, v11, vcc
	v_add_co_u32_e32 v14, vcc, s15, v10
	v_mov_b32_e32 v35, 0
	s_nop 0
	v_addc_co_u32_e32 v15, vcc, 0, v11, vcc
	v_add_co_u32_e32 v16, vcc, s16, v10
	s_mov_b32 s9, s10
	s_nop 0
	v_addc_co_u32_e32 v17, vcc, 0, v11, vcc
	v_add_co_u32_e32 v24, vcc, s17, v10
	s_nop 1
	v_addc_co_u32_e32 v25, vcc, 0, v11, vcc
	v_add_co_u32_e32 v26, vcc, 0x1e000, v10
	s_nop 1
	v_addc_co_u32_e32 v27, vcc, 0, v11, vcc
	v_add_co_u32_e32 v28, vcc, 0x24000, v10
	s_nop 1
	v_addc_co_u32_e32 v29, vcc, 0, v11, vcc
	v_add_co_u32_e32 v30, vcc, 0x2a000, v10
	s_nop 1
	v_addc_co_u32_e32 v31, vcc, 0, v11, vcc
	global_load_dword v22, v[10:11], off
	global_load_dword v23, v[12:13], off
	global_load_dword v32, v[14:15], off
	global_load_dword v19, v[24:25], off
	global_load_dword v21, v[26:27], off
	global_load_dword v34, v[28:29], off
	global_load_dword v36, v[30:31], off
	global_load_dword v33, v[16:17], off
	v_mov_b32_e32 v10, 0
	v_mov_b32_e32 v11, v5
	v_mov_b32_e32 v12, 0
	v_mov_b32_e32 v13, v5
	v_mov_b32_e32 v14, 0
	v_mov_b32_e32 v15, v5
	v_mov_b32_e32 v16, 0
	v_mov_b32_e32 v17, v5
	v_mov_b32_e32 v24, 0
	v_mov_b32_e32 v25, v5
	v_mov_b32_e32 v30, 0
	v_mov_b32_e32 v31, v5
	v_mov_b32_e32 v26, 0
	v_mov_b32_e32 v27, v5
	v_mov_b32_e32 v28, 0
	v_mov_b32_e32 v29, v5
	s_waitcnt vmcnt(4)
	v_mov_b32_e32 v37, v19
	s_waitcnt vmcnt(3)
	v_mov_b32_e32 v38, v21
	s_waitcnt vmcnt(2)
	v_mov_b32_e32 v39, v34
	s_waitcnt vmcnt(0)
	v_mov_b32_e32 v40, v36
	s_add_i32 s22, s9, 8
	s_cmp_ge_i32 s22, s12
	s_cbranch_scc1 .LBB0_24
	s_branch .LBB0_23
.LBB0_22:
	s_waitcnt vmcnt(0)
	v_mov_b32_e32 v22, v19
	v_mov_b32_e32 v23, v21
	v_mov_b32_e32 v19, v37
	v_mov_b32_e32 v21, v38
	v_mov_b32_e32 v32, v34
	v_mov_b32_e32 v33, v36
	v_mov_b32_e32 v34, v39
	v_mov_b32_e32 v36, v40
	s_add_i32 s22, s9, 8
	s_cmp_ge_i32 s22, s12
	s_cbranch_scc1 .LBB0_24

; #define LAS __attribute__((address_space(3)))
; __device__ __forceinline__ void phase_prologue(const Args& a, LAS unsigned char* lds, const WCtx& w) {
;     ...
;             for (int k = k0; k < k0 + 128; k += 4) {
;                 const float w0 = a0, w1 = a1, w2 = a2, w3 = a3; a0 = b0; a1 = b1; a2 = b2; a3 = b3;
;                 if (k + 8 < k0 + 128) { const float* wn = wp + (size_t)(k + 8) * 6144; b0 = wn[0]; b1 = wn[6144]; b2 = wn[2 * 6144]; b3 = wn[3 * 6144]; }
; #pragma unroll
;                 for (int r = 0; r < 17; ++r) { const f32x4 s = *(const LAS f32x4*)(SC + r * 1024 + k); acc[r] += (s[0] * w0 + s[1] * w1) + (s[2] * w2 + s[3] * w3); }
;             }
; #pragma unroll
;             for (int r = 0; r < 17; ++r) RED[(w.wave * 17 + r) * 64 + w.lane] = acc[r];
;             __syncthreads();
;             for (int i = w.tid; i < 17 * 64; i += NTHREADS) { const int r = i >> 6, col = i & 63; float s = 0.f;
; #pragma unroll
;                 for (int q = 0; q < 8; ++q) s += RED[(q * 17 + r) * 64 + col];
;                 MOD[(size_t)(l * 17 + r) * 6144 + cg * 64 + col] = s + a.in[I_ADAB][l * 6144 + cg * 64 + col]; }
.LBB0_24:
	v_mov_b32_e32 v41, s8
	ds_read_b128 v[42:45], v41 offset:8192
	ds_read_b128 v[46:49], v41 offset:4096
	ds_read_b128 v[50:53], v41
	ds_read_b128 v[54:57], v41 offset:12288
	s_add_i32 s22, s8, 0x10000
	s_waitcnt lgkmcnt(3)
	v_mov_b32_e32 v58, v42
	s_waitcnt lgkmcnt(2)
	v_mov_b32_e32 v59, v47
	v_pk_mul_f32 v[58:59], v[22:23], v[58:59]
	v_mov_b32_e32 v42, v43
	v_mov_b32_e32 v43, v46
	v_pk_fma_f32 v[46:47], v[22:23], v[42:43], v[58:59] op_sel:[1,0,0] op_sel_hi:[0,1,1]
	v_mov_b32_e32 v42, v44
	v_mov_b32_e32 v43, v49
	s_waitcnt vmcnt(4)
	v_pk_mul_f32 v[58:59], v[32:33], v[42:43]
	v_mov_b32_e32 v60, v45
	ds_read_b128 v[42:45], v41 offset:16384
	v_mov_b32_e32 v61, v48
	v_pk_fma_f32 v[48:49], v[32:33], v[60:61], v[58:59] op_sel:[1,0,0] op_sel_hi:[0,1,1]
	v_pk_add_f32 v[46:47], v[46:47], v[48:49]
	s_waitcnt lgkmcnt(1)
	v_mov_b32_e32 v59, v55
	v_pk_add_f32 v[30:31], v[30:31], v[46:47]
	ds_read_b128 v[46:49], v41 offset:20480
	s_waitcnt lgkmcnt(1)
	v_mov_b32_e32 v58, v42
	v_pk_mul_f32 v[58:59], v[22:23], v[58:59]
	v_mov_b32_e32 v42, v43
	v_mov_b32_e32 v43, v54
	v_pk_fma_f32 v[54:55], v[22:23], v[42:43], v[58:59] op_sel:[1,0,0] op_sel_hi:[0,1,1]
	v_mov_b32_e32 v42, v44
	v_mov_b32_e32 v43, v57
	v_pk_mul_f32 v[58:59], v[32:33], v[42:43]
	v_mov_b32_e32 v60, v45
	ds_read_b128 v[42:45], v41 offset:24576
	v_mov_b32_e32 v61, v56
	v_pk_fma_f32 v[56:57], v[32:33], v[60:61], v[58:59] op_sel:[1,0,0] op_sel_hi:[0,1,1]
	v_pk_add_f32 v[54:55], v[54:55], v[56:57]
	s_waitcnt lgkmcnt(1)
	v_mov_b32_e32 v59, v47
	v_pk_add_f32 v[24:25], v[24:25], v[54:55]
	ds_read_b128 v[54:57], v41 offset:28672
	s_waitcnt lgkmcnt(1)
	v_mov_b32_e32 v58, v42
	v_pk_mul_f32 v[58:59], v[22:23], v[58:59]
	v_mov_b32_e32 v42, v43
	v_mov_b32_e32 v43, v46
	v_pk_fma_f32 v[46:47], v[22:23], v[42:43], v[58:59] op_sel:[1,0,0] op_sel_hi:[0,1,1]
	v_mov_b32_e32 v42, v44
	v_mov_b32_e32 v43, v49
	v_pk_mul_f32 v[58:59], v[32:33], v[42:43]
	v_mov_b32_e32 v60, v45
	ds_read_b128 v[42:45], v41 offset:32768
	v_mov_b32_e32 v61, v48
	v_pk_fma_f32 v[48:49], v[32:33], v[60:61], v[58:59] op_sel:[1,0,0] op_sel_hi:[0,1,1]
	v_pk_add_f32 v[46:47], v[46:47], v[48:49]
	s_waitcnt lgkmcnt(1)
	v_mov_b32_e32 v59, v55
	v_pk_add_f32 v[16:17], v[16:17], v[46:47]
	ds_read_b128 v[46:49], v41 offset:36864
	s_waitcnt lgkmcnt(1)
	v_mov_b32_e32 v58, v42
	v_pk_mul_f32 v[58:59], v[22:23], v[58:59]
	v_mov_b32_e32 v42, v43
	v_mov_b32_e32 v43, v54
	v_pk_fma_f32 v[54:55], v[22:23], v[42:43], v[58:59] op_sel:[1,0,0] op_sel_hi:[0,1,1]
	v_mov_b32_e32 v42, v44
	v_mov_b32_e32 v43, v57
	v_pk_mul_f32 v[58:59], v[32:33], v[42:43]
	v_mov_b32_e32 v60, v45
	ds_read_b128 v[42:45], v41 offset:40960
	v_mov_b32_e32 v61, v56
	v_pk_fma_f32 v[56:57], v[32:33], v[60:61], v[58:59] op_sel:[1,0,0] op_sel_hi:[0,1,1]
	v_pk_add_f32 v[54:55], v[54:55], v[56:57]
	s_waitcnt lgkmcnt(1)
	v_mov_b32_e32 v59, v47
	v_pk_add_f32 v[14:15], v[14:15], v[54:55]
	ds_read_b128 v[54:57], v41 offset:45056
	s_waitcnt lgkmcnt(1)
	v_mov_b32_e32 v58, v42
	v_pk_mul_f32 v[58:59], v[22:23], v[58:59]
	v_mov_b32_e32 v42, v43
	v_mov_b32_e32 v43, v46
	v_pk_fma_f32 v[46:47], v[22:23], v[42:43], v[58:59] op_sel:[1,0,0] op_sel_hi:[0,1,1]
	v_mov_b32_e32 v42, v44
	v_mov_b32_e32 v43, v49
	v_pk_mul_f32 v[42:43], v[32:33], v[42:43]
	v_mov_b32_e32 v44, v45
	v_mov_b32_e32 v45, v48
	v_pk_fma_f32 v[48:49], v[32:33], v[44:45], v[42:43] op_sel:[1,0,0] op_sel_hi:[0,1,1]
	ds_read_b128 v[42:45], v41 offset:49152
	v_pk_add_f32 v[46:47], v[46:47], v[48:49]
	s_waitcnt lgkmcnt(1)
	v_mov_b32_e32 v58, v55
	v_pk_add_f32 v[12:13], v[12:13], v[46:47]
	ds_read_b128 v[46:49], v41 offset:53248
	s_waitcnt lgkmcnt(1)
	v_mov_b32_e32 v59, v42
	v_pk_mul_f32 v[58:59], v[22:23], v[58:59] op_sel:[1,0] op_sel_hi:[0,1]
	v_mov_b32_e32 v55, v43
	v_pk_fma_f32 v[42:43], v[22:23], v[54:55], v[58:59]
	v_mov_b32_e32 v54, v57
	v_mov_b32_e32 v55, v44
	v_pk_mul_f32 v[54:55], v[32:33], v[54:55] op_sel:[1,0] op_sel_hi:[0,1]
	v_mov_b32_e32 v57, v45
	v_pk_fma_f32 v[44:45], v[32:33], v[56:57], v[54:55]
	v_mov_b32_e32 v54, v53
	v_pk_add_f32 v[42:43], v[42:43], v[44:45]
	s_waitcnt lgkmcnt(0)
	v_mov_b32_e32 v55, v48
	v_pk_add_f32 v[10:11], v[10:11], v[42:43]
	v_mov_b32_e32 v42, v51
	v_mov_b32_e32 v51, v47
	v_mov_b32_e32 v43, v46
	v_pk_mul_f32 v[44:45], v[22:23], v[50:51]
	v_mov_b32_e32 v53, v49
	v_pk_fma_f32 v[50:51], v[22:23], v[42:43], v[44:45] op_sel:[1,0,0] op_sel_hi:[0,1,1]
	ds_read_b128 v[42:45], v41 offset:57344
	ds_read_b128 v[46:49], v41 offset:61440
	v_pk_mul_f32 v[52:53], v[32:33], v[52:53]
	v_mov_b32_e32 v41, s22
	v_pk_fma_f32 v[52:53], v[32:33], v[54:55], v[52:53] op_sel:[1,0,0] op_sel_hi:[0,1,1]
	v_pk_add_f32 v[50:51], v[50:51], v[52:53]
	s_add_i32 s9, s9, 4
	v_pk_add_f32 v[26:27], v[26:27], v[50:51]
	s_waitcnt lgkmcnt(1)
	v_mov_b32_e32 v50, v43
	s_waitcnt lgkmcnt(0)
	v_mov_b32_e32 v43, v47
	v_mov_b32_e32 v51, v46
	v_pk_mul_f32 v[42:43], v[22:23], v[42:43]
	s_add_i32 s8, s8, 16
	v_pk_fma_f32 v[46:47], v[22:23], v[50:51], v[42:43] op_sel:[1,0,0] op_sel_hi:[0,1,1]
	v_mov_b32_e32 v50, v45
	v_mov_b32_e32 v45, v49
	v_mov_b32_e32 v51, v48
	v_pk_mul_f32 v[48:49], v[32:33], v[44:45]
	ds_read_b128 v[42:45], v41
	v_pk_fma_f32 v[48:49], v[32:33], v[50:51], v[48:49] op_sel:[1,0,0] op_sel_hi:[0,1,1]
	v_pk_add_f32 v[46:47], v[46:47], v[48:49]
	s_cmp_ge_i32 s9, s12
	v_pk_add_f32 v[28:29], v[28:29], v[46:47]
	v_pk_mov_b32 v[46:47], v[22:23], v[32:33] op_sel:[1,0]
	s_waitcnt lgkmcnt(0)
	v_mov_b32_e32 v48, v43
	v_mov_b32_e32 v23, v33
	v_mov_b32_e32 v43, v45
	v_mov_b32_e32 v49, v44
	v_pk_mul_f32 v[22:23], v[22:23], v[42:43]
	s_nop 0
	v_pk_fma_f32 v[22:23], v[46:47], v[48:49], v[22:23]
	s_nop 0
	v_add_f32_e32 v22, v22, v23
	v_add_f32_e32 v35, v35, v22
	s_cbranch_scc0 .LBB0_22
	v_add_u32_e32 v8, s13, v1
	ds_write2st64_b32 v8, v26, v31 offset1:1
	ds_write2st64_b32 v8, v30, v25 offset0:2 offset1:3
	ds_write2st64_b32 v8, v24, v17 offset0:4 offset1:5
	ds_write2st64_b32 v8, v16, v15 offset0:6 offset1:7
	ds_write2st64_b32 v8, v14, v13 offset0:8 offset1:9
	ds_write2st64_b32 v8, v12, v10 offset0:10 offset1:11
	ds_write2st64_b32 v8, v11, v27 offset0:12 offset1:13
	ds_write2st64_b32 v8, v28, v29 offset0:14 offset1:15
	ds_write_b32 v8, v35 offset:4096
	s_waitcnt lgkmcnt(0)
	s_barrier
	s_and_saveexec_b64 s[8:9], s[4:5]
	s_cbranch_execz .LBB0_20
	s_load_dwordx16 s[56:71], s[0:1], 0x0
	s_mul_i32 s22, s20, 0x1800
	s_add_i32 s22, s6, s22
	v_or_b32_e32 v8, s22, v18
	v_ashrrev_i32_e32 v9, 31, v8
	s_mul_i32 s20, s20, 17
	s_waitcnt lgkmcnt(0)
	v_lshl_add_u64 v[8:9], v[8:9], 2, s[66:67]
	v_lshl_add_u64 v[10:11], s[6:7], 2, v[6:7]
	s_mov_b64 s[6:7], 0
	v_mov_b32_e32 v12, v20
